# k25: scan chunk loader on wave 1 issuing at the end of its step (after the triangular inverse), wave 2 keeps only its state-chain work
# speedup vs baseline: 1.0022x; 1.0022x over previous
.LBB0_843:
	s_or_b64 exec, exec, s[0:1]
.LBB0_844:
	s_cmp_lt_i32 s4, -1
	s_cbranch_scc1 .Linv_dma_skip
	s_cmpk_gt_i32 s4, 0x1f9
	s_cbranch_scc1 .Linv_dma_skip
	s_cmp_lg_u32 s4, -1
	s_cbranch_scc1 .Linv_dma_go
	s_mov_b32 s38, 0x26a00
	v_lshl_add_u32 v154, v148, 2, s38
	ds_read_b32 v150, v154
	ds_read_b32 v151, v154 offset:256
	ds_read_b32 v152, v154 offset:512
	ds_read_b32 v153, v154 offset:768
	ds_read_b32 v155, v154 offset:1024
	s_waitcnt lgkmcnt(0)
	v_readlane_b32 s64, v155, 0
	v_readlane_b32 s65, v155, 1
	v_readlane_b32 s66, v155, 2
	v_readlane_b32 s67, v155, 3
	v_readlane_b32 s68, v155, 4
	v_readlane_b32 s69, v155, 5
	v_readlane_b32 s70, v155, 6
	v_readlane_b32 s71, v155, 7
	v_readlane_b32 s44, v155, 8
	s_mov_b32 s45, 0
	s_mov_b64 s[14:15], 0x37f20000
	s_mov_b64 s[16:17], 0x37f24000
	s_mov_b64 s[18:19], 0x20000
	s_mov_b64 s[20:21], 0x24000
	s_mov_b64 s[22:23], 0x8020000
	s_mov_b64 s[24:25], 0x8024000
	s_mov_b64 s[26:27], 0xfa20000
	s_mov_b64 s[28:29], 0xfa24000
	s_mov_b64 s[30:31], 0x2000
	s_mov_b64 s[34:35], 0x4000
	s_mov_b64 s[40:41], 0x2205000
	s_mov_b64 s[46:47], 0x8000
	s_add_u32 s68, s68, s34
	s_addc_u32 s69, s69, s35
	s_mov_b32 s48, 5
	v_cmp_gt_u32_e64 s[42:43], 32, v148

.Linv_dma_done:
	s_or_b64 exec, exec, s[50:51]
	s_add_u32 s40, s40, 0x1000
	s_addc_u32 s41, s41, 0
	s_add_u32 s46, s46, 0x8000
	s_addc_u32 s47, s47, 0
	s_add_u32 s68, s68, s34
	s_addc_u32 s69, s69, s35
	s_add_i32 s48, s48, 1
.Linv_dma_skip:
	s_cmpk_gt_i32 s4, 0x1f9
	s_cbranch_scc1 .Linv_drain
	s_waitcnt vmcnt(22)
	s_branch .Linv_bar
